# k29: k28 + scan Q-tile staging writes (4 ds_write_b128) moved from the step header to the previous step's state-update phase (Q tile is only read before the mid-step barrier)
# speedup vs baseline: 1.0048x; 1.0029x over previous
; #define LAS __attribute__((address_space(3)))
; __device__ __forceinline__ void ret_item(LAS unsigned char* lds, const bf16_t* proj, bf16_t* OD, int b, int h, int dir, int vs, float lg2) {
;     const int tid = opaque_tid(), wid = __builtin_amdgcn_readfirstlane(tid >> 6), lane = tid & 63, l15 = lane & 15, g = lane >> 4, q4 = l15 >> 2, pp = l15 & 3;
;     const bf16_t* Qg = proj + (size_t)(b * SEQ) * R_IN + h * 256;
;     const bf16_t* Kg = Qg + 2048;
;     const bf16_t* Vg = proj + (size_t)(b * SEQ) * R_IN + 4096 + h * 512 + vs * 128;
;     bf16_t* Og = OD + (size_t)(b * SEQ) * 4096 + h * 512 + vs * 128 + 16 * wid + 4 * g;
;     f32x4 st[16];
; #pragma unroll
;     for (int i = 0; i < 16; ++i) st[i] = (f32x4){0.f, 0.f, 0.f, 0.f};
;     const int qrow = tid >> 5, qpc = tid & 31, vrow = tid >> 4, vpc = tid & 15;
;     bf16x8 pq[4], pk[4], pv[2];
;     const float c16 = __builtin_amdgcn_exp2f(16.f * lg2), c32 = c16 * c16, c48 = c32 * c16, cd = c32 * c32;
;     const float qdl = __builtin_amdgcn_exp2f((float)(dir ? 16 - l15 : l15 + 1) * lg2);
;     float kd8[8], d4[4];
; #pragma unroll
;     for (int r = 0; r < 4; ++r) d4[r] = __builtin_amdgcn_exp2f((float)(dir ? 4 * g + r - l15 : l15 - 4 * g - r) * lg2);
; #pragma unroll
;     for (int jj = 0; jj < 8; ++jj) kd8[jj] = __builtin_amdgcn_exp2f((float)(dir ? 8 * g + jj : 31 - 8 * g - jj) * lg2);
;     const int b3 = (l15 >> 3) & 1, sit = wid >> 1, sjt0 = 2 * (wid & 1), lo2 = 32 * (g & 1) + 8 * (g >> 1);
;     LAS unsigned char* pSk = lds + KS + (16 * sjt0 + l15) * RSQ + ((16 * g) ^ (32 * b3));
;     LAS unsigned char* pSq = lds + QS + (16 * sit + l15) * RSQ + (lo2 ^ (32 * b3));
;     LAS unsigned char* pCq = lds + QS + l15 * RSQ + ((16 * g) ^ (32 * b3));
;     LAS unsigned char* pIs = lds + SP + l15 * RSS + 16 * g;
; __global__ void __launch_bounds__(512, 2) mega_fwd(Params p) {
;     ...
;             for (int u = bx; u < 256; u += G) {
;                 const int xcd = u & 7, slot = u >> 3, bh = xcd * 4 + (slot >> 3), sub = slot & 7, dir = sub >> 2, vs = sub & 3, b = bh >> 3, h = bh & 7;
;                 const float e = p.r_dec[j * 16 + dir * 8 + h]; const float xg = __builtin_amdgcn_exp2f(-e);
;                 const float lg = -(xg * (1.f + xg * (0.5f + xg * (1.f / 3 + xg * (0.25f + xg * (0.2f + xg * (1.f / 6)))))));
;                 ret::ret_item(lds, proj, dir ? OB : OF, b, h, dir, vs, lg * 1.4426950408889634f);
.LBB0_139:
	s_lshl_b32 s16, s15, 2
	s_and_b32 s16, s16, 28
	s_ashr_i32 s17, s15, 6
	s_bfe_u32 s21, s15, 0x10005
	s_add_i32 s24, s16, s17
	s_lshl_b32 s16, s21, 3
	s_and_b32 s26, s24, 7
	s_or_b32 s16, s16, s14
	s_or_b32 s72, s16, s26
	v_readlane_b32 s36, v253, 0
	s_lshl_b64 s[16:17], s[72:73], 2
	v_readlane_b32 s48, v253, 12
	v_readlane_b32 s49, v253, 13
	s_add_u32 s16, s48, s16
	s_addc_u32 s17, s49, s17
	global_load_dword v0, v177, s[16:17]
	s_waitcnt vmcnt(14)
	v_mov_b32_e32 v1, v252
	v_readlane_b32 s37, v253, 1
	v_readfirstlane_b32 s17, v1
	s_ashr_i32 s20, s17, 6
	s_ashr_i32 s25, s17, 7
	s_lshl_b32 s17, s20, 1
	s_and_b32 s17, s17, 2
	s_or_b32 s18, s17, 1
	s_sub_i32 s27, s17, s25
	s_sub_i32 s19, s18, s25
	s_sub_i32 s28, s25, s18
	s_cmp_eq_u32 s21, 0
	s_cselect_b64 s[22:23], -1, 0
	v_bfe_u32 v2, v1, 4, 2
	s_and_b64 s[22:23], s[22:23], exec
	v_lshlrev_b32_e32 v41, 2, v2
	s_cselect_b32 s19, s28, s19
	s_sub_i32 s28, s25, s17
	v_and_b32_e32 v40, 15, v1
	s_waitcnt vmcnt(13)
	v_or_b32_e32 v7, 1, v41
	s_cmp_eq_u32 s21, 0
	v_sub_u32_e32 v3, 16, v40
	v_add_u32_e32 v4, 1, v40
	v_sub_co_u32_e32 v5, vcc, v41, v40
	v_sub_u32_e32 v6, v40, v41
	s_waitcnt vmcnt(12)
	v_sub_u32_e32 v8, v7, v40
	v_sub_u32_e32 v7, v40, v7
	s_cselect_b64 s[36:37], -1, 0
	v_cndmask_b32_e64 v3, v3, v4, s[36:37]
	v_cndmask_b32_e64 v4, v5, v6, s[36:37]
	v_cndmask_b32_e64 v5, v8, v7, s[36:37]
	v_mov_b32_e32 v7, 0x3e4ccccd
	v_or_b32_e32 v43, 2, v41
	v_sub_u32_e32 v9, v43, v40
	v_sub_u32_e32 v10, v40, v43
	v_cndmask_b32_e64 v6, v9, v10, s[36:37]
	v_cvt_f32_i32_e32 v4, v4
	v_cvt_f32_i32_e32 v5, v5
	v_cvt_f32_i32_e32 v6, v6
	v_cvt_f32_ubyte0_e32 v3, v3
	v_lshlrev_b32_e32 v176, 3, v2
	v_readlane_b32 s41, v253, 5
	s_and_b64 s[22:23], s[36:37], exec
	s_cselect_b32 s29, s7, s9
	s_cselect_b32 s41, s6, s8
	s_cselect_b32 s21, s28, s27
	s_lshl_b32 s22, s24, 9
	v_readlane_b32 s40, v253, 4
	s_and_b32 s22, s22, 0xfffff000
	s_bfe_i32 s40, s15, 0x10005
	s_ashr_i32 s23, s22, 31
	s_mul_i32 s27, s22, 0x6000
	s_mul_hi_i32 s24, s22, 0x6000
	s_add_u32 s28, s4, s27
	v_readlane_b32 s38, v253, 2
	s_addc_u32 s24, s5, s24
	s_lshl_b32 s27, s26, 9
	v_readlane_b32 s39, v253, 3
	s_add_u32 s38, s28, s27
	v_or_b32_e32 v42, 3, v41
	s_addc_u32 s39, s24, 0
	s_lshl_b64 s[22:23], s[22:23], 13
	v_sub_u32_e32 v11, v42, v40
	s_add_u32 s22, s41, s22
	s_addc_u32 s23, s29, s23
	s_lshl_b32 s29, s26, 10
	v_readlane_b32 s42, v253, 6
	s_add_u32 s41, s22, s29
	s_addc_u32 s42, s23, 0
	s_lshl_b32 s26, s20, 4
	s_ashr_i32 s27, s26, 31
	s_add_u32 s22, s28, s29
	s_addc_u32 s23, s24, 0
	s_lshl_b32 s24, s15, 5
	s_and_b32 s24, s24, 0x300
	s_add_u32 s28, s41, s24
	v_lshlrev_b32_e32 v58, 4, v2
	s_waitcnt vmcnt(0)
	v_exp_f32_e64 v0, -v0
	v_lshlrev_b32_e32 v2, 2, v1
	s_addc_u32 s29, s42, 0
	v_readlane_b32 s42, v254, 50
	v_fmamk_f32 v7, v0, 0x3e2aaaab, v7
	v_fmaak_f32 v7, v0, v7, 0x3e800000
	v_fmaak_f32 v7, v0, v7, 0x3eaaaaab
	v_fma_f32 v7, v0, v7, 0.5
	v_fma_f32 v7, v0, v7, 1.0
	v_mul_f32_e32 v0, v0, v7
	v_mul_f32_e32 v0, 0xbfb8aa3b, v0
	v_mul_f32_e32 v46, v0, v3
	v_mul_f32_e32 v3, v0, v4
	v_mul_f32_e32 v4, v0, v5
	v_exp_f32_e32 v200, v4
	v_mul_f32_e32 v4, v0, v6
	v_exp_f32_e32 v201, v4
	v_xor_b32_e32 v4, 31, v176
	v_cndmask_b32_e64 v4, v176, v4, s[36:37]
	v_cvt_f32_ubyte0_e32 v4, v4
	v_mul_f32_e32 v4, v0, v4
	v_exp_f32_e32 v50, v4
	v_or_b32_e32 v4, 1, v176
	v_xor_b32_e32 v5, 30, v176
	v_cndmask_b32_e64 v4, v4, v5, s[36:37]
	v_cvt_f32_ubyte0_e32 v4, v4
	v_mul_f32_e32 v4, v0, v4
	v_exp_f32_e32 v51, v4
	v_or_b32_e32 v4, 2, v176
	v_xor_b32_e32 v5, 29, v176
	v_cndmask_b32_e64 v4, v4, v5, s[36:37]
	v_cvt_f32_ubyte0_e32 v4, v4
	v_mul_f32_e32 v4, v0, v4
	v_exp_f32_e32 v52, v4
	v_or_b32_e32 v4, 3, v176
	v_xor_b32_e32 v5, 28, v176
	v_cndmask_b32_e64 v4, v4, v5, s[36:37]
	v_cvt_f32_ubyte0_e32 v4, v4
	v_mul_f32_e32 v4, v0, v4
	v_exp_f32_e32 v53, v4
	v_or_b32_e32 v4, 4, v176
	v_xor_b32_e32 v5, 27, v176
	v_cndmask_b32_e64 v4, v4, v5, s[36:37]
	v_cvt_f32_ubyte0_e32 v4, v4
	v_mul_f32_e32 v4, v0, v4
	v_exp_f32_e32 v54, v4
	v_or_b32_e32 v4, 5, v176
	v_xor_b32_e32 v5, 26, v176
	v_cndmask_b32_e64 v4, v4, v5, s[36:37]
	v_cvt_f32_ubyte0_e32 v4, v4
	v_mul_f32_e32 v4, v0, v4
	v_exp_f32_e32 v55, v4
	v_or_b32_e32 v4, 6, v176
	v_xor_b32_e32 v5, 25, v176
	v_exp_f32_e32 v199, v3
	v_sub_u32_e32 v3, v40, v42
	v_cndmask_b32_e64 v4, v4, v5, s[36:37]
	v_cndmask_b32_e64 v3, v11, v3, s[36:37]
	v_cvt_f32_ubyte0_e32 v4, v4
	v_cvt_f32_i32_e32 v3, v3
	v_mul_f32_e32 v4, v0, v4
	v_exp_f32_e32 v56, v4
	v_or_b32_e32 v4, 7, v176
	v_xor_b32_e32 v5, 24, v176
	v_cndmask_b32_e64 v4, v4, v5, s[36:37]
	v_cvt_f32_ubyte0_e32 v4, v4
	v_mul_f32_e32 v7, 0x41800000, v0
	v_mul_f32_e32 v3, v0, v3
	v_mul_f32_e32 v0, v0, v4
	v_exp_f32_e32 v57, v0
	v_lshlrev_b32_e32 v0, 1, v1
	v_and_b32_e32 v203, 32, v0
	v_lshrrev_b32_e32 v0, 2, v1
	v_and_b32_e32 v0, 8, v0
	v_and_b32_e32 v4, 32, v2
	s_lshl_b64 s[26:27], s[26:27], 1
	v_exp_f32_e32 v202, v3
	v_bfe_u32 v3, v1, 2, 2
	v_bitop3_b32 v61, v203, v4, v0 bitop3:0x36
	v_mov_b32_e32 v0, s42
	s_movk_i32 s41, 0x90
	s_add_u32 s26, s28, s26
	v_mad_u32_u24 v63, v40, s41, v0
	v_or_b32_e32 v0, v176, v3
	v_lshlrev_b32_e32 v3, 3, v1
	s_addc_u32 s27, s29, s27
	v_ashrrev_i32_e32 v162, 5, v1
	v_bitop3_b32 v59, v58, v2, 32 bitop3:0x78
	v_lshl_or_b32 v60, s25, 4, v40
	s_movk_i32 s29, 0x240
	v_mul_u32_u24_e32 v2, 0x110, v0
	s_add_i32 s25, 0, 0x12000
	v_and_b32_e32 v3, 24, v3
	v_add3_u32 v64, s25, v2, v3
	v_mul_lo_u32 v2, v162, s29
	v_lshlrev_b32_e32 v4, 4, v1
	v_add_u32_e32 v68, 0, v2
	v_and_b32_e32 v2, 0x1c0, v4
	v_ashrrev_i32_e32 v166, 4, v1
	v_mul_u32_u24_e32 v0, 0x240, v0
	v_lshrrev_b32_e32 v1, 3, v1
	v_add3_u32 v69, v68, v2, v3
	v_or_b32_e32 v2, v3, v2
; #define LAS __attribute__((address_space(3)))
; __device__ __forceinline__ void ret_item(LAS unsigned char* lds, const bf16_t* proj, bf16_t* OD, int b, int h, int dir, int vs, float lg2) {
;     ...
;     LAS unsigned char* pKe = lds + KS + (8 * g + q4) * RSQ + 8 * pp + 32 * (g & 1);
;     LAS unsigned char* pKo = lds + KS + (8 * g + q4) * RSQ + 8 * pp - 32 * (g & 1);
;     const int sb3 = (qrow >> 3) & 1;
;     LAS unsigned char* wQ = lds + QS + qrow * RSQ + ((16 * qpc) ^ (32 * sb3));
;     LAS unsigned char* wK0 = lds + KS + qrow * RSQ + ((64 * (qpc >> 2) + 8 * (qpc & 3)) ^ (32 * sb3));
;     LAS unsigned char* wK1 = lds + KS + qrow * RSQ + ((64 * (qpc >> 2) + 32 + 8 * (qpc & 3)) ^ (32 * sb3));
;     {   const int c0 = dir ? 63 : 0; const size_t t0 = (size_t)c0 * CH;
; #pragma unroll
;         for (int k = 0; k < 4; ++k) { pq[k] = *(const bf16x8*)(Qg + (t0 + qrow + 16 * k) * R_IN + qpc * 8); pk[k] = *(const bf16x8*)(Kg + (t0 + qrow + 16 * k) * R_IN + qpc * 8); }
; #pragma unroll
;         for (int k = 0; k < 2; ++k) pv[k] = *(const bf16x8*)(Vg + (t0 + vrow + 32 * k) * R_IN + vpc * 8);
;     ...
;             for (int tt = 0; tt < 2; ++tt) { const f32x4 sv = tt ? sa1 : sa0; const int dt = dir ? (sjt0 + tt - sit) : (sit - sjt0 - tt);
;                 const float cs = dt <= 0 ? 1.f : dt == 1 ? c16 : dt == 2 ? c32 : c48; float w[4];
; #pragma unroll
;                 for (int r = 0; r < 4; ++r) { const bool on = dt > 0 || (dt == 0 && (dir ? (4 * g + r > l15) : (l15 >= 4 * g + r))); w[r] = on ? sv[r] * d4[r] * cs : 0.f; }
	v_lshl_add_u64 v[160:161], s[26:27], 0, v[176:177]
	v_add3_u32 v204, 0, v0, v3
	v_and_b32_e32 v0, 0x1f0, v4
	v_and_b32_e32 v66, 32, v1
	s_movk_i32 s26, 0x1f0
	v_bitop3_b32 v70, v2, v1, 32 bitop3:0x72
	s_and_b32 s28, s40, 0xfc0
	v_mov_b32_e32 v1, v177
	v_bitop3_b32 v67, v4, v66, s26 bitop3:0x6c
	v_add_u32_e32 v2, s28, v162
	v_lshl_add_u64 v[168:169], s[38:39], 0, v[0:1]
	s_mov_b64 s[26:27], 0x1000
	v_lshl_add_u64 v[170:171], v[168:169], 0, s[26:27]
	v_mad_i64_i32 v[24:25], s[26:27], v2, s3, v[168:169]
	v_add_co_u32_e64 v8, s[38:39], s65, v24
	v_mad_i64_i32 v[26:27], s[26:27], v2, s3, v[170:171]
	s_nop 0
	v_addc_co_u32_e64 v9, s[38:39], 0, v25, s[38:39]
	v_add_co_u32_e64 v12, s[38:39], s65, v26
	s_add_u32 s22, s22, s24
	s_nop 0
	v_addc_co_u32_e64 v13, s[38:39], 0, v27, s[38:39]
	v_add_co_u32_e64 v16, s[38:39], s64, v24
	v_exp_f32_e32 v47, v7
	s_nop 0
	v_addc_co_u32_e64 v17, s[38:39], 0, v25, s[38:39]
	v_add_co_u32_e64 v20, s[38:39], s64, v26
	v_lshl_or_b32 v32, s17, 4, v40
	s_nop 0
	v_addc_co_u32_e64 v21, s[38:39], 0, v27, s[38:39]
	v_mul_lo_u32 v33, v60, s29
	global_load_dwordx4 v[0:3], v[24:25], off
	global_load_dwordx4 v[4:7], v[26:27], off
	v_add_co_u32_e64 v24, s[38:39], s70, v24
	s_addc_u32 s23, s23, 0
	v_lshlrev_b32_e32 v44, 4, v40
	v_mov_b32_e32 v45, v177
	v_addc_co_u32_e64 v25, s[38:39], 0, v25, s[38:39]
	v_mad_u32_u24 v71, v32, s29, 0
	v_add_u32_e32 v72, 0, v33
	v_lshl_add_u64 v[32:33], s[22:23], 0, v[44:45]
	s_mov_b64 s[22:23], 0x2000
	v_add_co_u32_e64 v28, s[38:39], s70, v26
	v_add_u32_e32 v34, s28, v166
	v_lshl_add_u64 v[172:173], v[32:33], 0, s[22:23]
	v_addc_co_u32_e64 v29, s[38:39], 0, v27, s[38:39]
	v_mad_i64_i32 v[32:33], s[22:23], v34, s3, v[172:173]
	v_add_co_u32_e64 v36, s[38:39], s64, v32
	global_load_dwordx4 v[8:11], v[8:9], off
	s_nop 0
	global_load_dwordx4 v[12:15], v[12:13], off
	v_addc_co_u32_e64 v37, s[38:39], 0, v33, s[38:39]
	global_load_dwordx4 v[16:19], v[16:17], off
	s_nop 0
	global_load_dwordx4 v[20:23], v[20:21], off
	s_nop 0
	global_load_dwordx4 v[24:27], v[24:25], off
	s_nop 0
	global_load_dwordx4 v[28:31], v[28:29], off
	s_nop 0
	global_load_dwordx4 v[32:35], v[32:33], off
	s_nop 0
	global_load_dwordx4 v[36:39], v[36:37], off
	v_mad_u32_u24 v62, v40, s29, 0
	s_lshl_b32 s29, s20, 5
	s_cmp_eq_u32 s21, 1
	s_cselect_b64 s[38:39], -1, 0
	s_cmp_eq_u32 s21, 2
	v_readlane_b32 s44, v253, 8
	v_readlane_b32 s45, v253, 9
	v_exp_f32_e32 v45, v46
	v_mul_lo_u32 v46, v60, s41
	s_cselect_b64 s[40:41], -1, 0
	s_cmp_gt_i32 s21, 0
	v_mul_f32_e32 v48, v47, v47
	s_movk_i32 s20, 0x110
	s_cselect_b64 s[44:45], -1, 0
	s_cmp_lg_u32 s21, 0
	v_mul_f32_e32 v49, v47, v48
	v_add3_u32 v205, s42, v176, v46
	v_mul_lo_u32 v46, v166, s20
	s_cselect_b64 s[20:21], -1, 0
	s_lshl_b32 s17, s17, 5
	v_cndmask_b32_e64 v60, v49, v48, s[40:41]
	s_cmp_eq_u32 s19, 1
	v_cndmask_b32_e64 v60, v60, v47, s[38:39]
	s_cselect_b64 s[38:39], -1, 0
	s_cmp_eq_u32 s19, 2
	s_cselect_b64 s[40:41], -1, 0
	s_cmp_gt_i32 s19, 0
	s_cselect_b64 s[52:53], -1, 0
	s_cmp_lg_u32 s19, 0
	v_readlane_b32 s50, v253, 14
	v_readlane_b32 s51, v253, 15
	v_cndmask_b32_e64 v206, 1.0, v60, s[44:45]
	v_cndmask_b32_e64 v60, v49, v48, s[40:41]
	s_cselect_b64 s[22:23], -1, 0
	s_xor_b64 s[26:27], s[36:37], vcc
	v_cmp_le_u32_e32 vcc, v43, v40
	v_cndmask_b32_e64 v60, v60, v47, s[38:39]
	v_cmp_ge_u32_e64 s[38:39], v40, v41
	s_xor_b64 s[50:51], s[36:37], vcc
	v_cmp_le_u32_e32 vcc, v42, v40
	v_readlane_b32 s43, v253, 7
	v_add_u32_e32 v44, s25, v44
	s_xor_b64 s[24:25], s[36:37], s[38:39]
	s_xor_b64 s[76:77], s[36:37], vcc
	v_lshlrev_b32_e32 v224, 12, v40
	v_cndmask_b32_e64 v40, v49, 1.0, s[36:37]
	s_nor_b64 s[38:39], s[20:21], s[24:25]
	s_nor_b64 s[40:41], s[20:21], s[26:27]
	s_nor_b64 s[42:43], s[20:21], s[50:51]
	s_nor_b64 s[20:21], s[20:21], s[76:77]
	v_readlane_b32 s46, v253, 10
	v_readlane_b32 s47, v253, 11
	v_mul_f32_e32 v178, v45, v40
; #define LAS __attribute__((address_space(3)))
; __device__ __forceinline__ void ret_item(LAS unsigned char* lds, const bf16_t* proj, bf16_t* OD, int b, int h, int dir, int vs, float lg2) {
;     ...
;     f32x4 st[16];
; #pragma unroll
;     for (int i = 0; i < 16; ++i) st[i] = (f32x4){0.f, 0.f, 0.f, 0.f};
;     const int qrow = tid >> 5, qpc = tid & 31, vrow = tid >> 4, vpc = tid & 15;
;     bf16x8 pq[4], pk[4], pv[2];
;     const float c16 = __builtin_amdgcn_exp2f(16.f * lg2), c32 = c16 * c16, c48 = c32 * c16, cd = c32 * c32;
;     const float qdl = __builtin_amdgcn_exp2f((float)(dir ? 16 - l15 : l15 + 1) * lg2);
;     float kd8[8], d4[4];
; #pragma unroll
;     for (int r = 0; r < 4; ++r) d4[r] = __builtin_amdgcn_exp2f((float)(dir ? 4 * g + r - l15 : l15 - 4 * g - r) * lg2);
; #pragma unroll
;     for (int jj = 0; jj < 8; ++jj) kd8[jj] = __builtin_amdgcn_exp2f((float)(dir ? 8 * g + jj : 31 - 8 * g - jj) * lg2);
;     const int b3 = (l15 >> 3) & 1, sit = wid >> 1, sjt0 = 2 * (wid & 1), lo2 = 32 * (g & 1) + 8 * (g >> 1);
;     ...
;         for (int k = 0; k < 4; ++k) { *(LAS bf16x8*)(wQ + 16 * k * RSQ) = pq[k];
;             *(LAS s16x4*)(wK0 + 16 * k * RSQ) = (s16x4){pk[k][0], pk[k][1], pk[k][2], pk[k][3]}; *(LAS s16x4*)(wK1 + 16 * k * RSQ) = (s16x4){pk[k][4], pk[k][5], pk[k][6], pk[k][7]}; }
; #pragma unroll
;         for (int k = 0; k < 2; ++k) *(LAS bf16x8*)(lds + VS + (vrow + 32 * k) * RSV + vpc * 16) = pv[k];
	v_cndmask_b32_e64 v40, v48, v47, s[36:37]
	s_or_b64 s[38:39], s[44:45], s[38:39]
	s_or_b64 s[40:41], s[44:45], s[40:41]
	s_or_b64 s[42:43], s[44:45], s[42:43]
	s_or_b64 s[44:45], s[44:45], s[20:21]
	s_nor_b64 s[20:21], s[22:23], s[24:25]
	v_mul_f32_e32 v182, v45, v40
	v_cndmask_b32_e64 v40, v47, v48, s[36:37]
	s_or_b64 s[46:47], s[52:53], s[20:21]
	s_nor_b64 s[20:21], s[22:23], s[26:27]
	v_cndmask_b32_e64 v207, 1.0, v60, s[52:53]
	v_cndmask_b32_e64 v60, 1.0, v48, s[36:37]
	v_mul_f32_e32 v186, v45, v40
	v_cndmask_b32_e64 v40, 1.0, v49, s[36:37]
	s_or_b64 s[48:49], s[52:53], s[20:21]
	s_nor_b64 s[20:21], s[22:23], s[50:51]
	v_mul_f32_e32 v164, v48, v48
	v_sub_u32_e32 v65, 0, v203
	v_mul_f32_e32 v208, v50, v60
	v_mul_f32_e32 v209, v51, v60
	v_mul_f32_e32 v210, v52, v60
	v_mul_f32_e32 v211, v53, v60
	v_mul_f32_e32 v212, v54, v60
	v_mul_f32_e32 v213, v55, v60
	v_mul_f32_e32 v214, v56, v60
	v_mul_f32_e32 v215, v57, v60
	v_cndmask_b32_e64 v60, v48, 1.0, s[36:37]
	v_mul_f32_e32 v190, v45, v40
	s_or_b64 s[50:51], s[52:53], s[20:21]
	s_nor_b64 s[20:21], s[22:23], s[76:77]
	v_mov_b32_e32 v40, 0
	s_mov_b32 s16, 1
	v_ashrrev_i32_e32 v163, 31, v162
	v_ashrrev_i32_e32 v167, 31, v166
	v_mov_b32_e32 v174, v164
	v_mov_b32_e32 v175, v164
	s_lshl_b32 s18, s18, 5
	v_mul_f32_e32 v216, v50, v60
	v_mul_f32_e32 v217, v51, v60
	v_mul_f32_e32 v218, v52, v60
	v_mul_f32_e32 v219, v53, v60
	v_mul_f32_e32 v220, v54, v60
	v_mul_f32_e32 v221, v55, v60
	v_mul_f32_e32 v222, v56, v60
	v_mul_f32_e32 v223, v57, v60
	v_mov_b32_e32 v179, v178
	v_mov_b32_e32 v180, v178
	v_mov_b32_e32 v181, v178
	v_mov_b32_e32 v183, v182
	v_mov_b32_e32 v184, v182
	v_mov_b32_e32 v185, v182
	v_mov_b32_e32 v187, v186
	v_mov_b32_e32 v188, v186
	v_mov_b32_e32 v189, v186
	v_mov_b32_e32 v191, v190
	v_mov_b32_e32 v192, v190
	v_mov_b32_e32 v193, v190
	s_or_b64 s[52:53], s[52:53], s[20:21]
	s_mov_b32 s19, 62
	v_add_u32_e32 v225, v68, v67
	v_add_u32_e32 v226, v69, v66
	v_add_u32_e32 v227, v68, v70
	v_add_u32_e32 v228, v44, v46
	v_add_u32_e32 v229, v72, v61
	v_add_u32_e32 v230, v71, v59
	v_add_u32_e32 v231, v62, v59
	v_add_u32_e32 v232, s29, v64
	v_add_u32_e32 v233, v63, v58
	v_add_u32_e32 v234, v204, v65
	v_mov_b32_e32 v41, v40
	v_mov_b32_e32 v42, v40
	v_mov_b32_e32 v43, v40
	v_mov_b32_e32 v52, v40
	v_mov_b32_e32 v53, v40
	v_mov_b32_e32 v54, v40
	v_mov_b32_e32 v55, v40
	v_mov_b32_e32 v48, v40
	v_mov_b32_e32 v49, v40
	v_mov_b32_e32 v50, v40
	v_mov_b32_e32 v51, v40
	v_mov_b32_e32 v44, v40
	v_mov_b32_e32 v45, v40
	v_mov_b32_e32 v46, v40
	v_mov_b32_e32 v47, v40
	v_mov_b32_e32 v68, v40
	v_mov_b32_e32 v69, v40
	v_mov_b32_e32 v70, v40
	v_mov_b32_e32 v71, v40
	v_mov_b32_e32 v64, v40
	v_mov_b32_e32 v65, v40
	v_mov_b32_e32 v66, v40
	v_mov_b32_e32 v67, v40
	v_mov_b32_e32 v60, v40
	v_mov_b32_e32 v61, v40
	v_mov_b32_e32 v62, v40
	v_mov_b32_e32 v63, v40
	v_mov_b32_e32 v56, v40
	v_mov_b32_e32 v57, v40
	v_mov_b32_e32 v58, v40
	v_mov_b32_e32 v59, v40
	v_mov_b32_e32 v88, v40
	v_mov_b32_e32 v89, v40
	v_mov_b32_e32 v90, v40
	v_mov_b32_e32 v91, v40
	v_mov_b32_e32 v80, v40
	v_mov_b32_e32 v81, v40
	v_mov_b32_e32 v82, v40
	v_mov_b32_e32 v83, v40
	v_mov_b32_e32 v76, v40
	v_mov_b32_e32 v77, v40
	v_mov_b32_e32 v78, v40
	v_mov_b32_e32 v79, v40
	v_mov_b32_e32 v72, v40
	v_mov_b32_e32 v73, v40
	v_mov_b32_e32 v74, v40
	v_mov_b32_e32 v75, v40
	v_mov_b32_e32 v92, v40
	v_mov_b32_e32 v93, v40
	v_mov_b32_e32 v94, v40
	v_mov_b32_e32 v95, v40
	v_mov_b32_e32 v84, v40
	v_mov_b32_e32 v85, v40
	v_mov_b32_e32 v86, v40
	v_mov_b32_e32 v87, v40
	v_mov_b32_e32 v96, v40
	v_mov_b32_e32 v97, v40
	v_mov_b32_e32 v98, v40
	v_mov_b32_e32 v99, v40
	v_mov_b32_e32 v100, v40
	v_mov_b32_e32 v101, v40
	v_mov_b32_e32 v102, v40
	v_mov_b32_e32 v103, v40
	s_waitcnt vmcnt(0)
	ds_write_b128 v225, v[0:3]
	ds_write_b128 v225, v[8:11] offset:9216
	ds_write_b128 v225, v[16:19] offset:18432
	ds_write_b128 v225, v[24:27] offset:27648
	s_branch .LBB0_141

; #define LAS __attribute__((address_space(3)))
; __device__ __forceinline__ unsigned cvtpk(float lo, float hi) { unsigned r; asm volatile("v_cvt_pk_bf16_f32 %0, %1, %2" : "=v"(r) : "v"(lo), "v"(hi)); return r; }
; __device__ __forceinline__ bf16x8 cat(s16x4 a, s16x4 b) { return (bf16x8){a[0], a[1], a[2], a[3], b[0], b[1], b[2], b[3]}; }
; #define MF16(a, b, c) __builtin_amdgcn_mfma_f32_16x16x32_bf16((a), (b), (c), 0, 0, 0)
; #define SCHED() __builtin_amdgcn_sched_barrier(0)
; __device__ __forceinline__ void ret_item(LAS unsigned char* lds, const bf16_t* proj, bf16_t* OD, int b, int h, int dir, int vs, float lg2) {
;     ...
;             LDS_S(0, 0);
; #pragma unroll
;             for (int s = 0; s < 8; ++s) { if (s < 7) LDS_S((s + 1) & 1, s + 1); SCHED();
;                 const bf16x8 bq = cat(fq[s & 1][0], fq[s & 1][1]);
;                 __builtin_amdgcn_s_setprio(1); sa0 = MF16(fk0[s & 1], bq, sa0); sa1 = MF16(fk1[s & 1], bq, sa1); __builtin_amdgcn_s_setprio(0); SCHED(); }
;     ...
; #pragma unroll
;             for (int tt = 0; tt < 2; ++tt) { const f32x4 sv = tt ? sa1 : sa0; const int dt = dir ? (sjt0 + tt - sit) : (sit - sjt0 - tt);
;                 const float cs = dt <= 0 ? 1.f : dt == 1 ? c16 : dt == 2 ? c32 : c48; float w[4];
; #pragma unroll
;                 for (int r = 0; r < 4; ++r) { const bool on = dt > 0 || (dt == 0 && (dir ? (4 * g + r > l15) : (l15 >= 4 * g + r))); w[r] = on ? sv[r] * d4[r] * cs : 0.f; }
;                 u32x2 pkd; pkd.x = cvtpk(w[0], w[1]); pkd.y = cvtpk(w[2], w[3]);
;                 *(LAS u32x2*)(lds + SP + (16 * sit + l15) * RSS + (16 * (sjt0 + tt) + 4 * g) * 2) = pkd; }
;     ...
;         {   bf16x8 ca[2][4];
;     ...
;             LDS_C(0, 0);
; #pragma unroll
;             for (int s = 0; s < 8; ++s) { if (s < 7) LDS_C((s + 1) & 1, s + 1); SCHED();
;                 u32x4 bw; bw.x = cvtpk(st[2 * s][0], st[2 * s][1]); bw.y = cvtpk(st[2 * s][2], st[2 * s][3]); bw.z = cvtpk(st[2 * s + 1][0], st[2 * s + 1][1]); bw.w = cvtpk(st[2 * s + 1][2], st[2 * s + 1][3]);
;                 const bf16x8 bs = __builtin_bit_cast(bf16x8, bw);
;                 __builtin_amdgcn_s_setprio(1);
; #pragma unroll
;                 for (int it = 0; it < 4; ++it) acc[it] = MF16(bs, ca[s & 1][it], acc[it]);
;                 __builtin_amdgcn_s_setprio(0); SCHED(); }
.Lscan_pf_skip3:
	s_setprio 1
	s_waitcnt lgkmcnt(4)
	v_mfma_f32_16x16x32_bf16 v[108:111], v[120:123], v[116:119], v[108:111]
	s_waitcnt lgkmcnt(3)
	v_mfma_f32_16x16x32_bf16 v[104:107], v[124:127], v[116:119], v[104:107]
	s_setprio 0
	ds_read2_b64 v[116:119], v229 offset0:40 offset1:42
	ds_read_b128 v[120:123], v230 offset:37184
	ds_read_b128 v[124:127], v230 offset:46400
	s_setprio 1
	s_waitcnt lgkmcnt(4)
	v_mfma_f32_16x16x32_bf16 v[108:111], v[128:131], v[112:115], v[108:111]
	s_waitcnt lgkmcnt(3)
	v_mfma_f32_16x16x32_bf16 v[104:107], v[132:135], v[112:115], v[104:107]
	s_setprio 0
	ds_read2_b64 v[112:115], v229 offset0:48 offset1:50
	ds_read_b128 v[128:131], v230 offset:37248
	ds_read_b128 v[132:135], v230 offset:46464
	s_setprio 1
	s_waitcnt lgkmcnt(4)
	v_mfma_f32_16x16x32_bf16 v[108:111], v[120:123], v[116:119], v[108:111]
	s_waitcnt lgkmcnt(3)
	v_mfma_f32_16x16x32_bf16 v[104:107], v[124:127], v[116:119], v[104:107]
	s_setprio 0
	ds_read2_b64 v[116:119], v229 offset0:56 offset1:58
	ds_read_b128 v[120:123], v230 offset:37312
	ds_read_b128 v[124:127], v230 offset:46528
	s_setprio 1
	s_waitcnt lgkmcnt(4)
	v_mfma_f32_16x16x32_bf16 v[108:111], v[128:131], v[112:115], v[108:111]
	s_waitcnt lgkmcnt(3)
	v_mfma_f32_16x16x32_bf16 v[104:107], v[132:135], v[112:115], v[104:107]
	s_setprio 0
	s_setprio 1
	s_waitcnt lgkmcnt(1)
	v_mfma_f32_16x16x32_bf16 v[108:111], v[120:123], v[116:119], v[108:111]
	s_waitcnt lgkmcnt(0)
	v_mfma_f32_16x16x32_bf16 v[104:107], v[124:127], v[116:119], v[104:107]
	s_setprio 0
	s_nop 4
	v_mul_f32_e32 v108, v199, v108
	v_mul_f32_e32 v109, v200, v109
	v_mul_f32_e32 v110, v201, v110
	v_mul_f32_e32 v108, v206, v108
	v_mul_f32_e32 v109, v206, v109
	v_mul_f32_e32 v110, v206, v110
	v_mul_f32_e32 v111, v202, v111
	v_mul_f32_e32 v104, v199, v104
	v_mul_f32_e32 v105, v200, v105
	v_mul_f32_e32 v106, v201, v106
	v_cndmask_b32_e64 v108, 0, v108, s[38:39]
	v_cndmask_b32_e64 v109, 0, v109, s[40:41]
	v_cndmask_b32_e64 v110, 0, v110, s[42:43]
	v_mul_f32_e32 v111, v206, v111
	v_mul_f32_e32 v104, v207, v104
	v_mul_f32_e32 v105, v207, v105
	v_mul_f32_e32 v106, v207, v106
	v_mul_f32_e32 v107, v202, v107
	v_cndmask_b32_e64 v111, 0, v111, s[44:45]
	v_cvt_pk_bf16_f32 v108, v108, v109
	v_cvt_pk_bf16_f32 v109, v110, v111
	v_add_u32_e32 v110, s17, v205
	v_cndmask_b32_e64 v104, 0, v104, s[46:47]
	v_cndmask_b32_e64 v105, 0, v105, s[48:49]
	v_cndmask_b32_e64 v106, 0, v106, s[50:51]
	v_mul_f32_e32 v107, v207, v107
	ds_write_b64 v110, v[108:109]
	v_cndmask_b32_e64 v107, 0, v107, s[52:53]
	v_cvt_pk_bf16_f32 v104, v104, v105
	v_cvt_pk_bf16_f32 v105, v106, v107
	v_add_u32_e32 v106, s18, v205
	ds_write_b64 v106, v[104:105]
	ds_read_b128 v[104:107], v231
	ds_read_b128 v[108:111], v231 offset:64
	ds_read_b128 v[112:115], v231 offset:9216
	ds_read_b128 v[116:119], v231 offset:9280
	ds_read_b128 v[120:123], v231 offset:18432
	ds_read_b128 v[124:127], v231 offset:18496
	ds_read_b128 v[128:131], v231 offset:27648
	ds_read_b128 v[132:135], v231 offset:27712
	v_cvt_pk_bf16_f32 v136, v40, v41
	v_cvt_pk_bf16_f32 v137, v42, v43
	v_cvt_pk_bf16_f32 v138, v52, v53
	v_cvt_pk_bf16_f32 v139, v54, v55
	s_setprio 1
	s_waitcnt lgkmcnt(7)
	v_mfma_f32_16x16x32_bf16 v[104:107], v[136:139], v[104:107], 0
	s_waitcnt lgkmcnt(5)
	v_mfma_f32_16x16x32_bf16 v[112:115], v[136:139], v[112:115], 0
	s_waitcnt lgkmcnt(3)
	v_mfma_f32_16x16x32_bf16 v[120:123], v[136:139], v[120:123], 0
	s_waitcnt lgkmcnt(1)
	v_mfma_f32_16x16x32_bf16 v[128:131], v[136:139], v[128:131], 0
	s_setprio 0
	ds_read_b128 v[136:139], v231 offset:128
	ds_read_b128 v[140:143], v231 offset:9344
	ds_read_b128 v[144:147], v231 offset:18560
	ds_read_b128 v[148:151], v231 offset:27776
	v_cvt_pk_bf16_f32 v152, v48, v49
	v_cvt_pk_bf16_f32 v153, v50, v51
	v_cvt_pk_bf16_f32 v154, v44, v45
	v_cvt_pk_bf16_f32 v155, v46, v47
	s_setprio 1
	v_mfma_f32_16x16x32_bf16 v[104:107], v[152:155], v[108:111], v[104:107]
	v_mfma_f32_16x16x32_bf16 v[108:111], v[152:155], v[116:119], v[112:115]
	v_mfma_f32_16x16x32_bf16 v[112:115], v[152:155], v[124:127], v[120:123]
	s_waitcnt lgkmcnt(4)
	v_mfma_f32_16x16x32_bf16 v[116:119], v[152:155], v[132:135], v[128:131]
	s_setprio 0
	ds_read_b128 v[120:123], v231 offset:192
	ds_read_b128 v[124:127], v231 offset:9408
	ds_read_b128 v[128:131], v231 offset:18624
	ds_read_b128 v[132:135], v231 offset:27840
	v_cvt_pk_bf16_f32 v152, v68, v69
	v_cvt_pk_bf16_f32 v153, v70, v71
	v_cvt_pk_bf16_f32 v154, v64, v65
	v_cvt_pk_bf16_f32 v155, v66, v67
	s_setprio 1
	s_waitcnt lgkmcnt(7)
	v_mfma_f32_16x16x32_bf16 v[104:107], v[152:155], v[136:139], v[104:107]
	s_waitcnt lgkmcnt(6)
	v_mfma_f32_16x16x32_bf16 v[108:111], v[152:155], v[140:143], v[108:111]
	s_waitcnt lgkmcnt(5)
	v_mfma_f32_16x16x32_bf16 v[112:115], v[152:155], v[144:147], v[112:115]
	s_waitcnt lgkmcnt(4)
	v_mfma_f32_16x16x32_bf16 v[116:119], v[152:155], v[148:151], v[116:119]
	s_setprio 0
	ds_read_b128 v[136:139], v231 offset:256
	ds_read_b128 v[140:143], v231 offset:9472
	ds_read_b128 v[144:147], v231 offset:18688
	ds_read_b128 v[148:151], v231 offset:27904
	v_cvt_pk_bf16_f32 v152, v60, v61
	v_cvt_pk_bf16_f32 v153, v62, v63
	v_cvt_pk_bf16_f32 v154, v56, v57
	v_cvt_pk_bf16_f32 v155, v58, v59
	s_setprio 1
	s_waitcnt lgkmcnt(7)
	v_mfma_f32_16x16x32_bf16 v[104:107], v[152:155], v[120:123], v[104:107]
	s_waitcnt lgkmcnt(6)
	v_mfma_f32_16x16x32_bf16 v[108:111], v[152:155], v[124:127], v[108:111]
	s_waitcnt lgkmcnt(5)
	v_mfma_f32_16x16x32_bf16 v[112:115], v[152:155], v[128:131], v[112:115]
	s_waitcnt lgkmcnt(4)
; #define LAS __attribute__((address_space(3)))
; __device__ __forceinline__ unsigned cvtpk(float lo, float hi) { unsigned r; asm volatile("v_cvt_pk_bf16_f32 %0, %1, %2" : "=v"(r) : "v"(lo), "v"(hi)); return r; }
; __device__ __forceinline__ s16x4 trd(LAS unsigned char* p) { return __builtin_bit_cast(s16x4, __builtin_amdgcn_ds_read_tr16_b64_v4i16((LAS s16x4*)p)); }
; __device__ __forceinline__ bf16x8 cat(s16x4 a, s16x4 b) { return (bf16x8){a[0], a[1], a[2], a[3], b[0], b[1], b[2], b[3]}; }
; #define MF16(a, b, c) __builtin_amdgcn_mfma_f32_16x16x32_bf16((a), (b), (c), 0, 0, 0)
; __device__ __forceinline__ unsigned cvtpk(float lo, float hi) { unsigned r; asm volatile("v_cvt_pk_bf16_f32 %0, %1, %2" : "=v"(r) : "v"(lo), "v"(hi)); return r; }
; #define SCHED() __builtin_amdgcn_sched_barrier(0)
; __device__ __forceinline__ void ret_item(LAS unsigned char* lds, const bf16_t* proj, bf16_t* OD, int b, int h, int dir, int vs, float lg2) {
;     ...
;         {   bf16x8 ca[2][4];
;     ...
;             LDS_C(0, 0);
; #pragma unroll
;             for (int s = 0; s < 8; ++s) { if (s < 7) LDS_C((s + 1) & 1, s + 1); SCHED();
;                 u32x4 bw; bw.x = cvtpk(st[2 * s][0], st[2 * s][1]); bw.y = cvtpk(st[2 * s][2], st[2 * s][3]); bw.z = cvtpk(st[2 * s + 1][0], st[2 * s + 1][1]); bw.w = cvtpk(st[2 * s + 1][2], st[2 * s + 1][3]);
;                 const bf16x8 bs = __builtin_bit_cast(bf16x8, bw);
;                 __builtin_amdgcn_s_setprio(1);
; #pragma unroll
;                 for (int it = 0; it < 4; ++it) acc[it] = MF16(bs, ca[s & 1][it], acc[it]);
;                 __builtin_amdgcn_s_setprio(0); SCHED(); }
;     ...
;         }
;         bf16x8 bv[2], ia[2][4];
; #pragma unroll
;         for (int s = 0; s < 2; ++s) { bv[s] = cat(trd(pVt + 32 * s * RSV), trd(pVt + (32 * s + 4) * RSV));
; #pragma unroll
;             for (int it = 0; it < 4; ++it) ia[s][it] = *(const LAS bf16x8*)(pIs + 16 * it * RSS + 64 * s); }
;         s16x4 ua[2][4][2];
;     ...
;         LDS_U(0, 0);
;         SCHED();
; #pragma unroll
;         for (int it = 0; it < 4; ++it) { const int ex = dir ? 3 - it : it; const float cq = qdl * (ex == 0 ? 1.f : ex == 1 ? c16 : ex == 2 ? c32 : c48); acc[it] = acc[it] * cq; }
; #pragma unroll
;         for (int s = 0; s < 2; ++s)
; #pragma unroll
;             for (int it = 0; it < 4; ++it) acc[it] = MF16(bv[s], ia[s][it], acc[it]);
	v_mfma_f32_16x16x32_bf16 v[116:119], v[152:155], v[132:135], v[116:119]
	s_setprio 0
	ds_read_b128 v[120:123], v231 offset:320
	ds_read_b128 v[124:127], v231 offset:9536
	ds_read_b128 v[128:131], v231 offset:18752
	ds_read_b128 v[132:135], v231 offset:27968
	v_cvt_pk_bf16_f32 v152, v88, v89
	v_cvt_pk_bf16_f32 v153, v90, v91
	v_cvt_pk_bf16_f32 v154, v80, v81
	v_cvt_pk_bf16_f32 v155, v82, v83
	s_setprio 1
	s_waitcnt lgkmcnt(7)
	v_mfma_f32_16x16x32_bf16 v[104:107], v[152:155], v[136:139], v[104:107]
	s_waitcnt lgkmcnt(6)
	v_mfma_f32_16x16x32_bf16 v[108:111], v[152:155], v[140:143], v[108:111]
	s_waitcnt lgkmcnt(5)
	v_mfma_f32_16x16x32_bf16 v[112:115], v[152:155], v[144:147], v[112:115]
	s_waitcnt lgkmcnt(4)
	v_mfma_f32_16x16x32_bf16 v[116:119], v[152:155], v[148:151], v[116:119]
	s_setprio 0
	ds_read_b128 v[136:139], v231 offset:384
	ds_read_b128 v[140:143], v231 offset:9600
	ds_read_b128 v[144:147], v231 offset:18816
	ds_read_b128 v[148:151], v231 offset:28032
	v_cvt_pk_bf16_f32 v152, v76, v77
	v_cvt_pk_bf16_f32 v153, v78, v79
	v_cvt_pk_bf16_f32 v154, v72, v73
	v_cvt_pk_bf16_f32 v155, v74, v75
	s_setprio 1
	s_waitcnt lgkmcnt(7)
	v_mfma_f32_16x16x32_bf16 v[104:107], v[152:155], v[120:123], v[104:107]
	s_waitcnt lgkmcnt(6)
	v_mfma_f32_16x16x32_bf16 v[108:111], v[152:155], v[124:127], v[108:111]
	s_waitcnt lgkmcnt(5)
	v_mfma_f32_16x16x32_bf16 v[112:115], v[152:155], v[128:131], v[112:115]
	s_waitcnt lgkmcnt(4)
	v_mfma_f32_16x16x32_bf16 v[116:119], v[152:155], v[132:135], v[116:119]
	s_setprio 0
	ds_read_b128 v[120:123], v231 offset:448
	ds_read_b128 v[124:127], v231 offset:9664
	ds_read_b128 v[128:131], v231 offset:18880
	ds_read_b128 v[132:135], v231 offset:28096
	v_cvt_pk_bf16_f32 v152, v92, v93
	v_cvt_pk_bf16_f32 v153, v94, v95
	v_cvt_pk_bf16_f32 v154, v84, v85
	v_cvt_pk_bf16_f32 v155, v86, v87
	s_setprio 1
	s_waitcnt lgkmcnt(7)
	v_mfma_f32_16x16x32_bf16 v[104:107], v[152:155], v[136:139], v[104:107]
	s_waitcnt lgkmcnt(6)
	v_mfma_f32_16x16x32_bf16 v[108:111], v[152:155], v[140:143], v[108:111]
	s_waitcnt lgkmcnt(5)
	v_mfma_f32_16x16x32_bf16 v[112:115], v[152:155], v[144:147], v[112:115]
	s_waitcnt lgkmcnt(4)
	v_mfma_f32_16x16x32_bf16 v[116:119], v[152:155], v[148:151], v[116:119]
	s_setprio 0
	v_cvt_pk_bf16_f32 v136, v96, v97
	v_cvt_pk_bf16_f32 v137, v98, v99
	v_cvt_pk_bf16_f32 v138, v100, v101
	v_cvt_pk_bf16_f32 v139, v102, v103
	s_setprio 1
	s_waitcnt lgkmcnt(3)
	v_mfma_f32_16x16x32_bf16 v[104:107], v[136:139], v[120:123], v[104:107]
	s_waitcnt lgkmcnt(2)
	v_mfma_f32_16x16x32_bf16 v[108:111], v[136:139], v[124:127], v[108:111]
	s_waitcnt lgkmcnt(1)
	v_mfma_f32_16x16x32_bf16 v[112:115], v[136:139], v[128:131], v[112:115]
	s_waitcnt lgkmcnt(0)
	v_mfma_f32_16x16x32_bf16 v[116:119], v[136:139], v[132:135], v[116:119]
	s_setprio 0
	s_waitcnt lgkmcnt(0)
	s_barrier
	ds_read_b64_tr_b16 v[140:141], v232
	ds_read_b64_tr_b16 v[142:143], v232 offset:1088
	ds_read_b64_tr_b16 v[136:137], v232 offset:8704
	ds_read_b64_tr_b16 v[138:139], v232 offset:9792
	ds_read_b128 v[144:147], v233
	ds_read_b128 v[148:151], v233 offset:64
	ds_read_b128 v[152:155], v233 offset:2304
	ds_read_b128 v[156:159], v233 offset:2368
	ds_read_b128 v[236:239], v233 offset:4608
	ds_read_b128 v[240:243], v233 offset:4672
	ds_read_b128 v[244:247], v233 offset:6912
	ds_read_b128 v[248:251], v233 offset:6976
	v_add_u32_e32 v235, v204, v203
	ds_read_b64_tr_b16 v[128:129], v235 offset:36864
	ds_read_b64_tr_b16 v[130:131], v235 offset:39168
	ds_read_b64_tr_b16 v[126:127], v235 offset:39232
	ds_read_b64_tr_b16 v[124:125], v235 offset:36928
	ds_read_b64_tr_b16 v[132:133], v234 offset:36896
	ds_read_b64_tr_b16 v[134:135], v234 offset:39200
	ds_read_b64_tr_b16 v[122:123], v234 offset:39264
	ds_read_b64_tr_b16 v[120:121], v234 offset:36960
	v_pk_mul_f32 v[106:107], v[180:181], v[106:107]
	v_pk_mul_f32 v[104:105], v[178:179], v[104:105]
	v_pk_mul_f32 v[114:115], v[188:189], v[114:115]
	v_pk_mul_f32 v[112:113], v[186:187], v[112:113]
	s_waitcnt lgkmcnt(14)
	v_mfma_f32_16x16x32_bf16 v[104:107], v[140:143], v[144:147], v[104:107]
	v_mul_f32_e64 v110, v184, v110
	v_mul_f32_e64 v111, v185, v111
	v_pk_mul_f32 v[108:109], v[182:183], v[108:109]
	s_waitcnt lgkmcnt(11)
	v_mfma_f32_16x16x32_bf16 v[144:147], v[140:143], v[236:239], v[112:115]
	s_nop 2
	v_mul_f32_e64 v114, v192, v118
	v_mul_f32_e64 v115, v193, v119
	v_pk_mul_f32 v[112:113], v[190:191], v[116:117]
	v_mfma_f32_16x16x32_bf16 v[108:111], v[140:143], v[152:155], v[108:111]
	s_waitcnt lgkmcnt(9)
	v_mfma_f32_16x16x32_bf16 v[152:155], v[140:143], v[244:247], v[112:115]
	v_mfma_f32_16x16x32_bf16 v[116:119], v[136:139], v[148:151], v[104:107]
	v_mfma_f32_16x16x32_bf16 v[112:115], v[136:139], v[156:159], v[108:111]
	v_mfma_f32_16x16x32_bf16 v[108:111], v[136:139], v[240:243], v[144:147]
	s_waitcnt lgkmcnt(8)
; __device__ __forceinline__ unsigned cvtpk(float lo, float hi) { unsigned r; asm volatile("v_cvt_pk_bf16_f32 %0, %1, %2" : "=v"(r) : "v"(lo), "v"(hi)); return r; }
; __device__ __forceinline__ bf16x8 cat(s16x4 a, s16x4 b) { return (bf16x8){a[0], a[1], a[2], a[3], b[0], b[1], b[2], b[3]}; }
; #define MF16(a, b, c) __builtin_amdgcn_mfma_f32_16x16x32_bf16((a), (b), (c), 0, 0, 0)
; __device__ __forceinline__ unsigned cvtpk(float lo, float hi) { unsigned r; asm volatile("v_cvt_pk_bf16_f32 %0, %1, %2" : "=v"(r) : "v"(lo), "v"(hi)); return r; }
; #define SCHED() __builtin_amdgcn_sched_barrier(0)
; #define LDS_U(buf, u) do { _Pragma("unroll") for (int k = 0; k < 4; ++k) { LAS unsigned char* pb = ((k & 1) ? pKo : pKe) + 32 * ((u) >> 2) * RSQ + 32 * (4 * ((u) & 3) + k); ua[buf][k][0] = trd(pb); ua[buf][k][1] = trd(pb + 4 * RSQ); } } while (0)
; __device__ __forceinline__ void ret_item(LAS unsigned char* lds, const bf16_t* proj, bf16_t* OD, int b, int h, int dir, int vs, float lg2) {
;     ...
;         for (int it = 0; it < 4; ++it) { const int ex = dir ? 3 - it : it; const float cq = qdl * (ex == 0 ? 1.f : ex == 1 ? c16 : ex == 2 ? c32 : c48); acc[it] = acc[it] * cq; }
; #pragma unroll
;         for (int s = 0; s < 2; ++s)
; #pragma unroll
;             for (int it = 0; it < 4; ++it) acc[it] = MF16(bv[s], ia[s][it], acc[it]);
;         SCHED();
; #pragma unroll
;         for (int i = 0; i < 16; ++i) st[i] = st[i] * cd;
;         bf16x8 bvd[2];
; #pragma unroll
;         for (int s = 0; s < 2; ++s) { const float ck = (dir ? s : 1 - s) ? c32 : 1.f; float e[8];
; #pragma unroll
;             for (int jj = 0; jj < 8; ++jj) e[jj] = bf2f((unsigned short)bv[s][jj]) * (kd8[jj] * ck);
;             u32x4 bw; bw.x = cvtpk(e[0], e[1]); bw.y = cvtpk(e[2], e[3]); bw.z = cvtpk(e[4], e[5]); bw.w = cvtpk(e[6], e[7]);
;             bvd[s] = __builtin_bit_cast(bf16x8, bw); }
; #pragma unroll
;         for (int u = 0; u < 8; ++u) { if (u < 7) LDS_U((u + 1) & 1, u + 1); SCHED();
;             __builtin_amdgcn_s_setprio(1);
; #pragma unroll
;             for (int k = 0; k < 4; ++k) st[4 * (u & 3) + k] = MF16(cat(ua[u & 1][k][0], ua[u & 1][k][1]), bvd[u >> 2], st[4 * (u & 3) + k]);
	v_mfma_f32_16x16x32_bf16 v[104:107], v[136:139], v[248:251], v[152:155]
	v_mov_b32_e32 v165, v164
	s_nop 1
	v_pk_mul_f32 v[154:155], v[164:165], v[46:47]
	v_pk_mul_f32 v[152:153], v[174:175], v[44:45]
	v_pk_mul_f32 v[46:47], v[164:165], v[70:71]
	v_pk_mul_f32 v[44:45], v[174:175], v[68:69]
	v_pk_mul_f32 v[158:159], v[164:165], v[58:59]
	v_pk_mul_f32 v[156:157], v[174:175], v[56:57]
	v_pk_mul_f32 v[70:71], v[164:165], v[82:83]
	v_pk_mul_f32 v[68:69], v[174:175], v[80:81]
	v_pk_mul_f32 v[82:83], v[164:165], v[78:79]
	v_pk_mul_f32 v[80:81], v[174:175], v[76:77]
	v_pk_mul_f32 v[58:59], v[164:165], v[94:95]
	v_pk_mul_f32 v[56:57], v[174:175], v[92:93]
	v_pk_mul_f32 v[78:79], v[164:165], v[86:87]
	v_pk_mul_f32 v[76:77], v[174:175], v[84:85]
	v_lshlrev_b32_e32 v84, 16, v140
	v_and_b32_e32 v85, 0xffff0000, v140
	v_lshlrev_b32_e32 v86, 16, v141
	v_and_b32_e32 v87, 0xffff0000, v141
	v_lshlrev_b32_e32 v92, 16, v142
	v_and_b32_e32 v93, 0xffff0000, v142
	v_lshlrev_b32_e32 v94, 16, v143
	v_and_b32_e32 v95, 0xffff0000, v143
	v_mul_f32_e32 v84, v208, v84
	v_mul_f32_e32 v85, v209, v85
	v_mul_f32_e32 v86, v210, v86
	v_mul_f32_e32 v87, v211, v87
	v_mul_f32_e32 v92, v212, v92
	v_mul_f32_e32 v93, v213, v93
	v_mul_f32_e32 v94, v214, v94
	v_mul_f32_e32 v95, v215, v95
	v_pk_mul_f32 v[146:147], v[164:165], v[50:51]
	v_pk_mul_f32 v[144:145], v[174:175], v[48:49]
	v_pk_mul_f32 v[50:51], v[164:165], v[90:91]
	v_pk_mul_f32 v[48:49], v[174:175], v[88:89]
	v_pk_mul_f32 v[90:91], v[164:165], v[74:75]
	v_pk_mul_f32 v[88:89], v[174:175], v[72:73]
	v_pk_mul_f32 v[74:75], v[164:165], v[98:99]
	v_pk_mul_f32 v[72:73], v[174:175], v[96:97]
	v_cvt_pk_bf16_f32 v84, v84, v85
	v_cvt_pk_bf16_f32 v85, v86, v87
	v_cvt_pk_bf16_f32 v86, v92, v93
	v_cvt_pk_bf16_f32 v87, v94, v95
	v_lshlrev_b32_e32 v92, 16, v136
	v_and_b32_e32 v93, 0xffff0000, v136
	v_lshlrev_b32_e32 v94, 16, v137
	v_and_b32_e32 v95, 0xffff0000, v137
	v_lshlrev_b32_e32 v96, 16, v138
	v_and_b32_e32 v97, 0xffff0000, v138
	v_lshlrev_b32_e32 v98, 16, v139
	v_and_b32_e32 v99, 0xffff0000, v139
	v_mul_f32_e32 v92, v216, v92
	v_mul_f32_e32 v93, v217, v93
	v_mul_f32_e32 v94, v218, v94
	v_mul_f32_e32 v95, v219, v95
	v_mul_f32_e32 v96, v220, v96
	v_mul_f32_e32 v97, v221, v97
	v_mul_f32_e32 v98, v222, v98
	v_mul_f32_e32 v99, v223, v99
	v_pk_mul_f32 v[150:151], v[164:165], v[62:63]
	v_pk_mul_f32 v[148:149], v[174:175], v[60:61]
	v_pk_mul_f32 v[62:63], v[164:165], v[102:103]
	v_pk_mul_f32 v[60:61], v[174:175], v[100:101]
	v_cvt_pk_bf16_f32 v100, v92, v93
	v_cvt_pk_bf16_f32 v101, v94, v95
	v_cvt_pk_bf16_f32 v102, v96, v97
	v_cvt_pk_bf16_f32 v103, v98, v99
	ds_read_b64_tr_b16 v[92:93], v235 offset:36992
	ds_read_b64_tr_b16 v[94:95], v235 offset:39296
	ds_read_b64_tr_b16 v[96:97], v234 offset:37024
	ds_read_b64_tr_b16 v[98:99], v234 offset:39328
	ds_read_b64_tr_b16 v[136:137], v235 offset:37056
	ds_read_b64_tr_b16 v[138:139], v235 offset:39360
	ds_read_b64_tr_b16 v[140:141], v234 offset:37088
	ds_read_b64_tr_b16 v[142:143], v234 offset:39392
	v_pk_mul_f32 v[42:43], v[164:165], v[42:43]
	v_pk_mul_f32 v[40:41], v[174:175], v[40:41]
	v_pk_mul_f32 v[54:55], v[164:165], v[54:55]
	v_pk_mul_f32 v[52:53], v[174:175], v[52:53]
	v_pk_mul_f32 v[66:67], v[164:165], v[66:67]
	v_pk_mul_f32 v[64:65], v[174:175], v[64:65]
	s_setprio 1
	s_waitcnt lgkmcnt(14)
	v_mfma_f32_16x16x32_bf16 v[40:43], v[128:131], v[84:87], v[40:43]
	s_waitcnt lgkmcnt(10)
	v_mfma_f32_16x16x32_bf16 v[52:55], v[132:135], v[84:87], v[52:55]
	v_mfma_f32_16x16x32_bf16 v[124:127], v[124:127], v[84:87], v[144:147]
	s_waitcnt lgkmcnt(8)
	v_mfma_f32_16x16x32_bf16 v[120:123], v[120:123], v[84:87], v[152:155]
	s_setprio 0
	ds_read_b64_tr_b16 v[128:129], v235 offset:37120
	ds_read_b64_tr_b16 v[130:131], v235 offset:39424
	ds_read_b64_tr_b16 v[134:135], v235 offset:39488
	ds_read_b64_tr_b16 v[132:133], v235 offset:37184
	ds_read_b64_tr_b16 v[144:145], v234 offset:37152
	ds_read_b64_tr_b16 v[146:147], v234 offset:39456
	ds_read_b64_tr_b16 v[154:155], v234 offset:39520
	ds_read_b64_tr_b16 v[152:153], v234 offset:37216
	s_setprio 1
	s_waitcnt lgkmcnt(14)
	v_mfma_f32_16x16x32_bf16 v[92:95], v[92:95], v[84:87], v[44:47]
	s_waitcnt lgkmcnt(12)
	v_mfma_f32_16x16x32_bf16 v[64:67], v[96:99], v[84:87], v[64:67]
	s_waitcnt lgkmcnt(10)
	v_mfma_f32_16x16x32_bf16 v[96:99], v[136:139], v[84:87], v[148:151]
	s_waitcnt lgkmcnt(8)
	v_mfma_f32_16x16x32_bf16 v[136:139], v[140:143], v[84:87], v[156:159]
	s_setprio 0
	ds_read_b64_tr_b16 v[44:45], v235 offset:37248
	ds_read_b64_tr_b16 v[46:47], v235 offset:39552
	ds_read_b64_tr_b16 v[142:143], v235 offset:39616
	ds_read_b64_tr_b16 v[140:141], v235 offset:37312
	ds_read_b64_tr_b16 v[148:149], v234 offset:37280
	ds_read_b64_tr_b16 v[150:151], v234 offset:39584
	ds_read_b64_tr_b16 v[158:159], v234 offset:39648
	ds_read_b64_tr_b16 v[156:157], v234 offset:37344
	s_setprio 1
	s_waitcnt lgkmcnt(14)
	v_mfma_f32_16x16x32_bf16 v[128:131], v[128:131], v[84:87], v[48:51]
	s_waitcnt lgkmcnt(10)
	v_mfma_f32_16x16x32_bf16 v[144:147], v[144:147], v[84:87], v[68:71]
	v_mfma_f32_16x16x32_bf16 v[132:135], v[132:135], v[84:87], v[80:83]
	s_waitcnt lgkmcnt(8)
; #define LAS __attribute__((address_space(3)))
; __device__ __forceinline__ unsigned cvtpk(float lo, float hi) { unsigned r; asm volatile("v_cvt_pk_bf16_f32 %0, %1, %2" : "=v"(r) : "v"(lo), "v"(hi)); return r; }
; __device__ __forceinline__ bf16x8 cat(s16x4 a, s16x4 b) { return (bf16x8){a[0], a[1], a[2], a[3], b[0], b[1], b[2], b[3]}; }
; #define MF16(a, b, c) __builtin_amdgcn_mfma_f32_16x16x32_bf16((a), (b), (c), 0, 0, 0)
; #define RBAR() do { asm volatile("s_waitcnt lgkmcnt(0)" ::: "memory"); __builtin_amdgcn_s_barrier(); asm volatile("" ::: "memory"); } while (0)
; __device__ __forceinline__ unsigned cvtpk(float lo, float hi) { unsigned r; asm volatile("v_cvt_pk_bf16_f32 %0, %1, %2" : "=v"(r) : "v"(lo), "v"(hi)); return r; }
; #define SCHED() __builtin_amdgcn_sched_barrier(0)
; #define LDS_U(buf, u) do { _Pragma("unroll") for (int k = 0; k < 4; ++k) { LAS unsigned char* pb = ((k & 1) ? pKo : pKe) + 32 * ((u) >> 2) * RSQ + 32 * (4 * ((u) & 3) + k); ua[buf][k][0] = trd(pb); ua[buf][k][1] = trd(pb + 4 * RSQ); } } while (0)
; __device__ __forceinline__ void ret_item(LAS unsigned char* lds, const bf16_t* proj, bf16_t* OD, int b, int h, int dir, int vs, float lg2) {
;     ...
;         for (int k = 0; k < 4; ++k) { *(LAS bf16x8*)(wQ + 16 * k * RSQ) = pq[k];
;             *(LAS s16x4*)(wK0 + 16 * k * RSQ) = (s16x4){pk[k][0], pk[k][1], pk[k][2], pk[k][3]}; *(LAS s16x4*)(wK1 + 16 * k * RSQ) = (s16x4){pk[k][4], pk[k][5], pk[k][6], pk[k][7]}; }
;     ...
;         for (int u = 0; u < 8; ++u) { if (u < 7) LDS_U((u + 1) & 1, u + 1); SCHED();
;             __builtin_amdgcn_s_setprio(1);
; #pragma unroll
;             for (int k = 0; k < 4; ++k) st[4 * (u & 3) + k] = MF16(cat(ua[u & 1][k][0], ua[u & 1][k][1]), bvd[u >> 2], st[4 * (u & 3) + k]);
;             __builtin_amdgcn_s_setprio(0); SCHED(); }
;     ...
; #pragma unroll
;         for (int it = 0; it < 4; ++it) { u32x2 w; w.x = cvtpk(acc[it][0], acc[it][1]); w.y = cvtpk(acc[it][2], acc[it][3]); *(u32x2*)(Og + (t0 + 16 * it + l15) * 4096) = w; }
;         RBAR();
	v_mfma_f32_16x16x32_bf16 v[152:155], v[152:155], v[84:87], v[88:91]
	s_setprio 0
	ds_read_b64_tr_b16 v[48:49], v235 offset:55296
	ds_read_b64_tr_b16 v[50:51], v235 offset:57600
	ds_read_b64_tr_b16 v[70:71], v235 offset:57664
	ds_read_b64_tr_b16 v[68:69], v235 offset:55360
	ds_read_b64_tr_b16 v[80:81], v234 offset:55328
	ds_read_b64_tr_b16 v[82:83], v234 offset:57632
	ds_read_b64_tr_b16 v[90:91], v234 offset:57696
	ds_read_b64_tr_b16 v[88:89], v234 offset:55392
	s_setprio 1
	s_waitcnt lgkmcnt(14)
	v_mfma_f32_16x16x32_bf16 v[236:239], v[44:47], v[84:87], v[56:59]
	s_waitcnt lgkmcnt(10)
	v_mfma_f32_16x16x32_bf16 v[148:151], v[148:151], v[84:87], v[76:79]
	v_mfma_f32_16x16x32_bf16 v[140:143], v[140:143], v[84:87], v[72:75]
	s_waitcnt lgkmcnt(8)
	v_mfma_f32_16x16x32_bf16 v[156:159], v[156:159], v[84:87], v[60:63]
	s_setprio 0
	ds_read_b64_tr_b16 v[56:57], v235 offset:55424
	ds_read_b64_tr_b16 v[58:59], v235 offset:57728
	ds_read_b64_tr_b16 v[62:63], v235 offset:57792
	ds_read_b64_tr_b16 v[60:61], v235 offset:55488
	ds_read_b64_tr_b16 v[72:73], v234 offset:55456
	ds_read_b64_tr_b16 v[74:75], v234 offset:57760
	ds_read_b64_tr_b16 v[78:79], v234 offset:57824
	ds_read_b64_tr_b16 v[76:77], v234 offset:55520
	s_setprio 1
	s_waitcnt lgkmcnt(14)
	v_mfma_f32_16x16x32_bf16 v[40:43], v[48:51], v[100:103], v[40:43]
	s_waitcnt lgkmcnt(10)
	v_mfma_f32_16x16x32_bf16 v[52:55], v[80:83], v[100:103], v[52:55]
	v_mfma_f32_16x16x32_bf16 v[48:51], v[68:71], v[100:103], v[124:127]
	s_waitcnt lgkmcnt(8)
	v_mfma_f32_16x16x32_bf16 v[44:47], v[88:91], v[100:103], v[120:123]
	s_setprio 0
	ds_read_b64_tr_b16 v[80:81], v235 offset:55552
	ds_read_b64_tr_b16 v[82:83], v235 offset:57856
	ds_read_b64_tr_b16 v[86:87], v235 offset:57920
	ds_read_b64_tr_b16 v[84:85], v235 offset:55616
	ds_read_b64_tr_b16 v[120:121], v234 offset:55584
	ds_read_b64_tr_b16 v[122:123], v234 offset:57888
	ds_read_b64_tr_b16 v[126:127], v234 offset:57952
	ds_read_b64_tr_b16 v[124:125], v234 offset:55648
	s_setprio 1
	s_waitcnt lgkmcnt(14)
	v_mfma_f32_16x16x32_bf16 v[68:71], v[56:59], v[100:103], v[92:95]
	s_waitcnt lgkmcnt(10)
	v_mfma_f32_16x16x32_bf16 v[64:67], v[72:75], v[100:103], v[64:67]
	v_mfma_f32_16x16x32_bf16 v[60:63], v[60:63], v[100:103], v[96:99]
	s_waitcnt lgkmcnt(8)
	v_mfma_f32_16x16x32_bf16 v[56:59], v[76:79], v[100:103], v[136:139]
	s_setprio 0
	s_waitcnt vmcnt(3)
	ds_write_b128 v225, v[0:3]
	ds_write_b128 v225, v[8:11] offset:9216
	ds_write_b128 v225, v[16:19] offset:18432
	ds_write_b128 v225, v[24:27] offset:27648
	ds_read_b64_tr_b16 v[92:93], v235 offset:55680
	ds_read_b64_tr_b16 v[94:95], v235 offset:57984
	ds_read_b64_tr_b16 v[98:99], v235 offset:58048
	ds_read_b64_tr_b16 v[96:97], v235 offset:55744
	ds_read_b64_tr_b16 v[136:137], v234 offset:55712
	ds_read_b64_tr_b16 v[138:139], v234 offset:58016
	ds_read_b64_tr_b16 v[242:243], v234 offset:58080
	ds_read_b64_tr_b16 v[240:241], v234 offset:55776
	s_setprio 1
	s_waitcnt lgkmcnt(14)
	v_mfma_f32_16x16x32_bf16 v[88:91], v[80:83], v[100:103], v[128:131]
	v_lshl_or_b32 v176, v176, 18, v224
	v_cvt_pk_bf16_f32 v116, v116, v117
	v_cvt_pk_bf16_f32 v117, v118, v119
	v_lshl_add_u64 v[118:119], v[176:177], 1, v[160:161]
	global_store_dwordx2 v[118:119], v[116:117], off
	s_waitcnt lgkmcnt(10)
	v_mfma_f32_16x16x32_bf16 v[80:83], v[120:123], v[100:103], v[144:147]
	v_mfma_f32_16x16x32_bf16 v[76:79], v[84:87], v[100:103], v[132:135]
	v_cvt_pk_bf16_f32 v112, v112, v113
	v_cvt_pk_bf16_f32 v113, v114, v115
	v_ashrrev_i32_e32 v115, 31, v176
	v_mov_b32_e32 v114, v176
	v_lshl_add_u64 v[114:115], v[114:115], 1, v[160:161]
	s_mov_b32 s20, 0x20000
	v_add_co_u32_e32 v116, vcc, s20, v114
	s_mov_b32 s20, 0x40000
	s_nop 0
	v_addc_co_u32_e32 v117, vcc, 0, v115, vcc
	global_store_dwordx2 v[116:117], v[112:113], off
	s_waitcnt lgkmcnt(8)
	v_mfma_f32_16x16x32_bf16 v[72:75], v[124:127], v[100:103], v[152:155]
	s_setprio 0
	s_setprio 1
	v_cvt_pk_bf16_f32 v108, v108, v109
	v_cvt_pk_bf16_f32 v109, v110, v111
	v_add_co_u32_e32 v110, vcc, s20, v114
	s_add_i32 s19, s19, -1
	s_nop 0
	v_addc_co_u32_e32 v111, vcc, 0, v115, vcc
	global_store_dwordx2 v[110:111], v[108:109], off
	s_waitcnt lgkmcnt(6)
	v_mfma_f32_16x16x32_bf16 v[92:95], v[92:95], v[100:103], v[236:239]
	v_cvt_pk_bf16_f32 v104, v104, v105
	v_cvt_pk_bf16_f32 v105, v106, v107
	v_add_co_u32_e32 v106, vcc, s65, v114
	s_add_i32 s16, s16, 1
	s_nop 0
	v_addc_co_u32_e32 v107, vcc, 0, v115, vcc
	global_store_dwordx2 v[106:107], v[104:105], off
	s_waitcnt lgkmcnt(2)
	v_mfma_f32_16x16x32_bf16 v[84:87], v[136:139], v[100:103], v[148:151]
	v_mfma_f32_16x16x32_bf16 v[96:99], v[96:99], v[100:103], v[140:143]
	s_waitcnt lgkmcnt(0)
	v_mfma_f32_16x16x32_bf16 v[100:103], v[240:243], v[100:103], v[156:159]
	s_setprio 0
	s_waitcnt lgkmcnt(0)
	s_barrier
	s_cmp_lg_u32 s19, -2
	s_cbranch_scc0 .LBB0_138
.LBB0_141:
	v_add_co_u32_e64 v104, s[20:21], s19, 1
	s_and_b64 vcc, exec, s[20:21]
	s_waitcnt vmcnt(13)
	s_waitcnt vmcnt(12)
	ds_write_b64 v226, v[4:5] offset:36864
	s_waitcnt vmcnt(11)
	s_waitcnt vmcnt(10)
	ds_write_b64 v226, v[12:13] offset:46080
	ds_write2st64_b64 v227, v[6:7], v[14:15] offset0:72 offset1:90
	s_waitcnt vmcnt(9)
	s_waitcnt vmcnt(8)
	ds_write_b64 v226, v[20:21] offset:55296
	s_waitcnt vmcnt(7)
	s_waitcnt vmcnt(6)
	ds_write_b64 v226, v[28:29] offset:64512
	ds_write2st64_b64 v227, v[22:23], v[30:31] offset0:108 offset1:126
	s_waitcnt vmcnt(5)
	ds_write_b128 v228, v[32:35]
	s_waitcnt vmcnt(4)
	ds_write_b128 v228, v[36:39] offset:8704
	s_branch .LBB0_140
